# attention softmax (s-m)*c via packed f32 fma; first queue ticket per workgroup static (block index); G1 half tile 5-stage LDS ring
# speedup vs baseline: 1.0037x; 1.0020x over previous
.LBB0_481:
	s_or_b64 exec, exec, s[0:1]
	s_lshl_b32 s84, s46, 7
	s_lshl_b64 s[0:1], s[84:85], 2
	v_readlane_b32 s2, v254, 17
	s_add_u32 s62, s2, s0
	v_readlane_b32 s2, v254, 18
	s_addc_u32 s63, s2, s1
	s_lshl_b32 s84, s46, 8
	s_lshl_b64 s[2:3], s[84:85], 2
	v_readlane_b32 s4, v254, 33
	s_add_u32 s90, s4, s2
	v_readlane_b32 s2, v254, 34
	s_addc_u32 s91, s2, s3
	v_readlane_b32 s2, v254, 35
	s_add_u32 s56, s2, s0
	v_readlane_b32 s0, v254, 36
	s_addc_u32 s57, s0, s1
	s_lshl_b32 s0, s46, 9
	s_mov_b32 s1, s85
	s_mov_b32 s2, s0
	v_writelane_b32 v255, s2, 15
	s_lshl_b64 s[76:77], s[0:1], 2
	v_readlane_b32 s0, v254, 37
	v_writelane_b32 v255, s3, 16
	s_add_u32 s2, s0, s76
	v_readlane_b32 s0, v254, 38
	s_addc_u32 s3, s0, s77
	v_writelane_b32 v255, s2, 17
	s_mul_i32 s84, s46, 0x3e00
	s_lshl_b64 s[0:1], s[84:85], 2
	v_writelane_b32 v255, s3, 18
	v_readlane_b32 s2, v254, 39
	s_add_u32 s2, s2, s0
	v_readlane_b32 s0, v254, 40
	s_addc_u32 s3, s0, s1
	v_writelane_b32 v255, s2, 19
	v_readlane_b32 s0, v254, 41
	s_mul_i32 s1, s46, 0xf800
	v_writelane_b32 v255, s3, 20
	s_add_u32 s2, s0, s76
	v_readlane_b32 s0, v254, 42
	s_addc_u32 s3, s0, s77
	v_writelane_b32 v255, s2, 21
	v_readlane_b32 s0, v254, 43
	v_mov_b32_e32 v0, 0x3eb60549
	v_writelane_b32 v255, s3, 22
	s_add_u32 s2, s0, s76
	v_readlane_b32 s0, v254, 44
	s_addc_u32 s3, s0, s77
	v_writelane_b32 v255, s2, 23
	s_lshl_b32 s0, s46, 19
	s_lshl_b32 s47, s46, 2
	v_writelane_b32 v255, s3, 24
	v_writelane_b32 v255, s0, 25
	s_mul_hi_u32 s0, s46, 0xf800
	v_readlane_b32 s2, v255, 6
	s_add_u32 s2, s2, s1
	v_readlane_b32 s1, v255, 7
	v_mov_b32_e32 v2, 0x3e4ccccd
	s_addc_u32 s3, s1, s0
	v_cndmask_b32_e64 v130, v0, v2, s[8:9]
	v_writelane_b32 v255, s2, 26
	v_sub_f32_e32 v151, 1.0, v130
	s_waitcnt lgkmcnt(0)
	v_writelane_b32 v255, s3, 27
	s_barrier
	s_mov_b32 s32, 1
	s_branch .LBB0_485

.LBB0_485:
	s_barrier
	s_and_saveexec_b64 s[0:1], s[6:7]
	s_cbranch_execz .LBB0_489
	s_cmp_eq_u32 s32, 0
	s_cbranch_scc1 .Lq1_dyn
	s_mov_b32 s32, 0
	v_readlane_b32 s2, v254, 0
	s_nop 1
	v_mov_b32_e32 v0, s2
	ds_write_b32 v1, v0
	s_branch .LBB0_489
.Lq1_dyn:
	s_mov_b64 s[30:31], exec
	v_mbcnt_lo_u32_b32 v0, s30, 0
	v_mbcnt_hi_u32_b32 v0, s31, v0
	v_cmp_eq_u32_e32 vcc, 0, v0
	s_and_saveexec_b64 s[4:5], vcc
	s_cbranch_execz .LBB0_488
	s_bcnt1_i32_b64 s2, s[30:31]
	v_mov_b32_e32 v2, s2
	global_atomic_add v2, v1, v2, s[62:63] sc0
.LBB0_488:
	s_or_b64 exec, exec, s[4:5]
	s_waitcnt vmcnt(0)
	v_readfirstlane_b32 s2, v2
	s_nop 1
	v_add_u32_e32 v0, s2, v0
	v_add_u32_e32 v0, s33, v0
	ds_write_b32 v1, v0

.LBB0_517:
	v_mov_b32_e32 v220, 0x3e38aa3b
	v_mul_f32_e32 v222, 0xbe38aa3b, v163
	v_mul_f32_e32 v224, 0xbe38aa3b, v3
	v_pk_fma_f32 v[100:101], v[100:101], v[220:221], v[222:223] op_sel_hi:[1,0,0]
	v_pk_fma_f32 v[102:103], v[102:103], v[220:221], v[222:223] op_sel_hi:[1,0,0]
	v_pk_fma_f32 v[104:105], v[104:105], v[220:221], v[222:223] op_sel_hi:[1,0,0]
	v_pk_fma_f32 v[106:107], v[106:107], v[220:221], v[222:223] op_sel_hi:[1,0,0]
	v_pk_fma_f32 v[108:109], v[108:109], v[220:221], v[222:223] op_sel_hi:[1,0,0]
	v_pk_fma_f32 v[110:111], v[110:111], v[220:221], v[222:223] op_sel_hi:[1,0,0]
	v_pk_fma_f32 v[112:113], v[112:113], v[220:221], v[222:223] op_sel_hi:[1,0,0]
	v_pk_fma_f32 v[114:115], v[114:115], v[220:221], v[222:223] op_sel_hi:[1,0,0]
	v_pk_fma_f32 v[84:85], v[84:85], v[220:221], v[224:225] op_sel_hi:[1,0,0]
	v_pk_fma_f32 v[86:87], v[86:87], v[220:221], v[224:225] op_sel_hi:[1,0,0]
	v_pk_fma_f32 v[88:89], v[88:89], v[220:221], v[224:225] op_sel_hi:[1,0,0]
	v_pk_fma_f32 v[90:91], v[90:91], v[220:221], v[224:225] op_sel_hi:[1,0,0]
	v_pk_fma_f32 v[92:93], v[92:93], v[220:221], v[224:225] op_sel_hi:[1,0,0]
	v_pk_fma_f32 v[94:95], v[94:95], v[220:221], v[224:225] op_sel_hi:[1,0,0]
	v_pk_fma_f32 v[96:97], v[96:97], v[220:221], v[224:225] op_sel_hi:[1,0,0]
	v_pk_fma_f32 v[98:99], v[98:99], v[220:221], v[224:225] op_sel_hi:[1,0,0]
	v_exp_f32_e32 v104, v104
	v_exp_f32_e32 v167, v84
	v_exp_f32_e32 v105, v105
	v_exp_f32_e32 v106, v106
	v_exp_f32_e32 v168, v85
	v_exp_f32_e32 v107, v107
	v_add_f32_e32 v175, 0, v104
	v_exp_f32_e32 v176, v100
	v_exp_f32_e32 v169, v86
	v_add_f32_e32 v175, v105, v175
	v_exp_f32_e32 v101, v101
	v_add_f32_e32 v175, v106, v175
	v_exp_f32_e32 v102, v102
	v_exp_f32_e32 v170, v87
	v_add_f32_e32 v175, v107, v175
	v_exp_f32_e32 v103, v103
	v_add_f32_e32 v100, v176, v175
	v_exp_f32_e32 v108, v108
	v_exp_f32_e32 v88, v88
	v_add_f32_e32 v100, v101, v100
	v_exp_f32_e32 v109, v109
	v_add_f32_e32 v100, v102, v100
	v_exp_f32_e32 v110, v110
	v_exp_f32_e32 v89, v89
	v_add_f32_e32 v100, v103, v100
	v_exp_f32_e32 v111, v111
	v_add_f32_e32 v100, v108, v100
	v_exp_f32_e32 v112, v112
	v_exp_f32_e32 v90, v90
	v_add_f32_e32 v100, v109, v100
	v_exp_f32_e32 v113, v113
	v_add_f32_e32 v100, v110, v100
	v_exp_f32_e32 v114, v114
	v_exp_f32_e32 v91, v91
	v_add_f32_e32 v100, v111, v100
	v_exp_f32_e32 v115, v115
	v_add_f32_e32 v100, v112, v100
	v_exp_f32_e32 v171, v92
	v_add_f32_e32 v100, v113, v100
	v_add_f32_e32 v100, v114, v100
	v_exp_f32_e32 v172, v93
	v_add_f32_e32 v100, v115, v100
	v_fmac_f32_e32 v100, v166, v2
	v_add_f32_e32 v2, 0, v167
	v_exp_f32_e32 v173, v94
	v_add_f32_e32 v2, v168, v2
	v_add_f32_e32 v2, v169, v2
	v_exp_f32_e32 v174, v95
	v_add_f32_e32 v2, v170, v2
	v_add_f32_e32 v2, v88, v2
	v_exp_f32_e32 v96, v96
	v_add_f32_e32 v2, v89, v2
	v_add_f32_e32 v2, v90, v2
	v_exp_f32_e32 v97, v97
	v_add_f32_e32 v2, v91, v2
	v_add_f32_e32 v2, v171, v2
	v_exp_f32_e32 v98, v98
	v_add_f32_e32 v2, v172, v2
	v_add_f32_e32 v2, v173, v2
	v_exp_f32_e32 v99, v99
	v_add_f32_e32 v2, v174, v2
	v_add_f32_e32 v2, v96, v2
	v_add_f32_e32 v2, v97, v2
	v_add_f32_e32 v2, v98, v2
	v_add_f32_e32 v2, v99, v2
	v_fmac_f32_e32 v2, v165, v0
	v_add3_u32 v0, v164, v153, v152
	v_cvt_pk_bf16_f32 v95, v90, v91
	v_cvt_pk_bf16_f32 v87, v98, v99
	v_cvt_pk_bf16_f32 v98, v176, v101
	v_cvt_pk_bf16_f32 v91, v114, v115
	v_add_u32_e32 v101, v0, v158
	v_add_u32_e32 v114, v0, v160
	v_cvt_pk_bf16_f32 v94, v88, v89
	v_cvt_pk_bf16_f32 v86, v96, v97
	v_cvt_pk_bf16_f32 v96, v104, v105
	v_cvt_pk_bf16_f32 v97, v106, v107
	v_cvt_pk_bf16_f32 v99, v102, v103
	v_cvt_pk_bf16_f32 v88, v108, v109
	ds_read2st64_b64 v[102:105], v101 offset0:32 offset1:36
	ds_read2st64_b64 v[106:109], v114 offset0:32 offset1:36
	v_cvt_pk_bf16_f32 v90, v112, v113
	v_cvt_pk_bf16_f32 v92, v167, v168
	v_cvt_pk_bf16_f32 v93, v169, v170
	v_cvt_pk_bf16_f32 v89, v110, v111
	s_waitcnt lgkmcnt(0)
	v_mov_b32_e32 v112, v106
	v_mov_b32_e32 v113, v107
	v_mov_b32_e32 v106, v104
	v_mov_b32_e32 v107, v105
	v_mov_b32_e32 v110, v102
	v_mov_b32_e32 v111, v103
	v_mfma_f32_16x16x32_bf16 v[72:75], v[106:109], v[92:95], v[72:75]
	v_cvt_pk_bf16_f32 v84, v171, v172
	v_cvt_pk_bf16_f32 v85, v173, v174
	s_add_i32 s1, s1, 1
	v_mfma_f32_16x16x32_bf16 v[68:71], v[106:109], v[96:99], v[68:71]
	ds_read2st64_b64 v[102:105], v101 offset0:40 offset1:44
	ds_read2st64_b64 v[106:109], v114 offset0:40 offset1:44
	s_add_i32 s0, s0, 0x8000
	v_lshl_add_u64 v[122:123], v[122:123], 0, s[70:71]
	v_mfma_f32_16x16x32_bf16 v[80:83], v[110:113], v[92:95], v[80:83]
	v_lshl_add_u64 v[124:125], v[124:125], 0, s[70:71]
	v_lshl_add_u64 v[126:127], v[126:127], 0, s[70:71]
	v_lshl_add_u64 v[128:129], v[128:129], 0, s[70:71]
	v_mfma_f32_16x16x32_bf16 v[76:79], v[110:113], v[96:99], v[76:79]
	s_waitcnt lgkmcnt(0)
	v_mov_b32_e32 v112, v106
	v_mov_b32_e32 v113, v107
	v_mov_b32_e32 v106, v104
	v_mov_b32_e32 v107, v105
	v_mov_b32_e32 v110, v102
	v_mov_b32_e32 v111, v103
	v_mfma_f32_16x16x32_bf16 v[56:59], v[106:109], v[92:95], v[56:59]
	v_lshl_add_u64 v[132:133], v[132:133], 0, s[64:65]
	v_lshl_add_u64 v[134:135], v[134:135], 0, s[64:65]
	v_lshl_add_u64 v[136:137], v[136:137], 0, s[64:65]
	v_mfma_f32_16x16x32_bf16 v[52:55], v[106:109], v[96:99], v[52:55]
	ds_read2st64_b64 v[102:105], v101 offset0:48 offset1:52
	ds_read2st64_b64 v[106:109], v114 offset0:48 offset1:52
	v_lshl_add_u64 v[138:139], v[138:139], 0, s[64:65]
	s_cmp_lg_u32 s1, 4
	v_mfma_f32_16x16x32_bf16 v[64:67], v[110:113], v[92:95], v[64:67]
	v_mfma_f32_16x16x32_bf16 v[60:63], v[110:113], v[96:99], v[60:63]
	s_waitcnt lgkmcnt(0)
	v_mov_b32_e32 v112, v106
	v_mov_b32_e32 v113, v107
	v_mov_b32_e32 v106, v104
	v_mov_b32_e32 v107, v105
	v_mov_b32_e32 v110, v102
	v_mov_b32_e32 v111, v103
	v_mfma_f32_16x16x32_bf16 v[40:43], v[106:109], v[92:95], v[40:43]
	v_mfma_f32_16x16x32_bf16 v[36:39], v[106:109], v[96:99], v[36:39]
	ds_read2st64_b64 v[102:105], v101 offset0:56 offset1:60
	ds_read2st64_b64 v[106:109], v114 offset0:56 offset1:60
	v_add_u32_e32 v101, v0, v161
	v_mfma_f32_16x16x32_bf16 v[48:51], v[110:113], v[92:95], v[48:51]
	v_add_u32_e32 v0, v0, v162
	v_mfma_f32_16x16x32_bf16 v[44:47], v[110:113], v[96:99], v[44:47]
	s_waitcnt lgkmcnt(0)
	v_mov_b32_e32 v110, v102
	v_mov_b32_e32 v111, v103
	v_mov_b32_e32 v112, v106
	v_mov_b32_e32 v113, v107
	v_mov_b32_e32 v106, v104
	v_mov_b32_e32 v107, v105
	v_mfma_f32_16x16x32_bf16 v[32:35], v[110:113], v[92:95], v[32:35]
	v_mfma_f32_16x16x32_bf16 v[20:23], v[110:113], v[96:99], v[20:23]
	v_mfma_f32_16x16x32_bf16 v[24:27], v[106:109], v[92:95], v[24:27]
	ds_read2st64_b64 v[92:95], v101 offset0:32 offset1:36
	s_waitcnt lgkmcnt(0)
	v_mov_b32_e32 v102, v92
	v_mfma_f32_16x16x32_bf16 v[28:31], v[106:109], v[96:99], v[28:31]
	ds_read2st64_b64 v[96:99], v0 offset0:32 offset1:36
	v_mov_b32_e32 v103, v93
	s_waitcnt lgkmcnt(0)
	v_mov_b32_e32 v104, v96
	v_mov_b32_e32 v105, v97
	v_mov_b32_e32 v96, v94
	v_mov_b32_e32 v97, v95
	v_mfma_f32_16x16x32_bf16 v[80:83], v[102:105], v[84:87], v[80:83]
	s_nop 0
	v_mfma_f32_16x16x32_bf16 v[72:75], v[96:99], v[84:87], v[72:75]
	v_mfma_f32_16x16x32_bf16 v[68:71], v[96:99], v[88:91], v[68:71]
	ds_read2st64_b64 v[92:95], v101 offset0:40 offset1:44
	ds_read2st64_b64 v[96:99], v0 offset0:40 offset1:44
	v_mfma_f32_16x16x32_bf16 v[76:79], v[102:105], v[88:91], v[76:79]
	s_waitcnt lgkmcnt(0)
	v_mov_b32_e32 v102, v92
	v_mov_b32_e32 v104, v96
	v_mov_b32_e32 v105, v97
	v_mov_b32_e32 v96, v94
	v_mov_b32_e32 v97, v95
	v_mov_b32_e32 v103, v93
	s_nop 0
	v_mfma_f32_16x16x32_bf16 v[56:59], v[96:99], v[84:87], v[56:59]
	v_mfma_f32_16x16x32_bf16 v[52:55], v[96:99], v[88:91], v[52:55]
	ds_read2st64_b64 v[92:95], v101 offset0:48 offset1:52
	ds_read2st64_b64 v[96:99], v0 offset0:48 offset1:52
	v_mfma_f32_16x16x32_bf16 v[64:67], v[102:105], v[84:87], v[64:67]
	v_mfma_f32_16x16x32_bf16 v[60:63], v[102:105], v[88:91], v[60:63]
	s_waitcnt lgkmcnt(0)
	v_mov_b32_e32 v104, v96
	v_mov_b32_e32 v105, v97
	v_mov_b32_e32 v96, v94
	v_mov_b32_e32 v97, v95
	v_mov_b32_e32 v102, v92
	v_mov_b32_e32 v103, v93
	v_mfma_f32_16x16x32_bf16 v[40:43], v[96:99], v[84:87], v[40:43]
	v_mfma_f32_16x16x32_bf16 v[36:39], v[96:99], v[88:91], v[36:39]
	ds_read2st64_b64 v[92:95], v101 offset0:56 offset1:60
	ds_read2st64_b64 v[96:99], v0 offset0:56 offset1:60
	v_mfma_f32_16x16x32_bf16 v[48:51], v[102:105], v[84:87], v[48:51]
	v_mfma_f32_16x16x32_bf16 v[44:47], v[102:105], v[88:91], v[44:47]
	s_waitcnt lgkmcnt(0)
	v_mov_b32_e32 v102, v92
	v_mov_b32_e32 v103, v93
	v_mov_b32_e32 v104, v96
	v_mov_b32_e32 v105, v97
	v_mov_b32_e32 v96, v94
	v_mov_b32_e32 v97, v95
	v_mfma_f32_16x16x32_bf16 v[32:35], v[102:105], v[84:87], v[32:35]
	v_mfma_f32_16x16x32_bf16 v[20:23], v[102:105], v[88:91], v[20:23]
	v_mfma_f32_16x16x32_bf16 v[24:27], v[96:99], v[84:87], v[24:27]
	v_mfma_f32_16x16x32_bf16 v[28:31], v[96:99], v[88:91], v[28:31]
	s_cbranch_scc0 .LBB0_519
	v_mov_b32_e32 v165, v2
	v_mov_b32_e32 v166, v100
	v_mov_b32_e32 v100, v3
	v_mov_b32_e32 v2, v163
	s_branch .LBB0_511

.LBB0_623:
	v_mov_b32_e32 v220, 0x3e38aa3b
	v_mul_f32_e32 v222, 0xbe38aa3b, v133
	v_mul_f32_e32 v224, 0xbe38aa3b, v3
	v_pk_fma_f32 v[100:101], v[100:101], v[220:221], v[222:223] op_sel_hi:[1,0,0]
	v_pk_fma_f32 v[102:103], v[102:103], v[220:221], v[222:223] op_sel_hi:[1,0,0]
	v_pk_fma_f32 v[104:105], v[104:105], v[220:221], v[222:223] op_sel_hi:[1,0,0]
	v_pk_fma_f32 v[106:107], v[106:107], v[220:221], v[222:223] op_sel_hi:[1,0,0]
	v_pk_fma_f32 v[108:109], v[108:109], v[220:221], v[222:223] op_sel_hi:[1,0,0]
	v_pk_fma_f32 v[110:111], v[110:111], v[220:221], v[222:223] op_sel_hi:[1,0,0]
	v_pk_fma_f32 v[112:113], v[112:113], v[220:221], v[222:223] op_sel_hi:[1,0,0]
	v_pk_fma_f32 v[114:115], v[114:115], v[220:221], v[222:223] op_sel_hi:[1,0,0]
	v_pk_fma_f32 v[84:85], v[84:85], v[220:221], v[224:225] op_sel_hi:[1,0,0]
	v_pk_fma_f32 v[86:87], v[86:87], v[220:221], v[224:225] op_sel_hi:[1,0,0]
	v_pk_fma_f32 v[88:89], v[88:89], v[220:221], v[224:225] op_sel_hi:[1,0,0]
	v_pk_fma_f32 v[90:91], v[90:91], v[220:221], v[224:225] op_sel_hi:[1,0,0]
	v_pk_fma_f32 v[92:93], v[92:93], v[220:221], v[224:225] op_sel_hi:[1,0,0]
	v_pk_fma_f32 v[94:95], v[94:95], v[220:221], v[224:225] op_sel_hi:[1,0,0]
	v_pk_fma_f32 v[96:97], v[96:97], v[220:221], v[224:225] op_sel_hi:[1,0,0]
	v_pk_fma_f32 v[98:99], v[98:99], v[220:221], v[224:225] op_sel_hi:[1,0,0]
	v_exp_f32_e32 v104, v104
	v_exp_f32_e32 v137, v84
	v_exp_f32_e32 v105, v105
	v_exp_f32_e32 v106, v106
	v_exp_f32_e32 v139, v85
	v_exp_f32_e32 v107, v107
	v_add_f32_e32 v182, 0, v104
	v_exp_f32_e32 v183, v100
	v_exp_f32_e32 v141, v86
	v_add_f32_e32 v182, v105, v182
	v_exp_f32_e32 v101, v101
	v_add_f32_e32 v182, v106, v182
	v_exp_f32_e32 v102, v102
	v_exp_f32_e32 v143, v87
	v_add_f32_e32 v182, v107, v182
	v_exp_f32_e32 v103, v103
	v_add_f32_e32 v100, v183, v182
	v_exp_f32_e32 v108, v108
	v_exp_f32_e32 v88, v88
	v_add_f32_e32 v100, v101, v100
	v_exp_f32_e32 v109, v109
	v_add_f32_e32 v100, v102, v100
	v_exp_f32_e32 v110, v110
	v_exp_f32_e32 v89, v89
	v_add_f32_e32 v100, v103, v100
	v_exp_f32_e32 v111, v111
	v_add_f32_e32 v100, v108, v100
	v_exp_f32_e32 v112, v112
	v_exp_f32_e32 v90, v90
	v_add_f32_e32 v100, v109, v100
	v_exp_f32_e32 v113, v113
	v_add_f32_e32 v100, v110, v100
	v_exp_f32_e32 v114, v114
	v_exp_f32_e32 v91, v91
	v_add_f32_e32 v100, v111, v100
	v_exp_f32_e32 v115, v115
	v_add_f32_e32 v100, v112, v100
	v_exp_f32_e32 v145, v92
	v_add_f32_e32 v100, v113, v100
	v_add_f32_e32 v100, v114, v100
	v_exp_f32_e32 v147, v93
	v_add_f32_e32 v100, v115, v100
	v_fmac_f32_e32 v100, v179, v2
	v_add_f32_e32 v2, 0, v137
	v_exp_f32_e32 v180, v94
	v_add_f32_e32 v2, v139, v2
	v_add_f32_e32 v2, v141, v2
	v_exp_f32_e32 v181, v95
	v_add_f32_e32 v2, v143, v2
	v_add_f32_e32 v2, v88, v2
	v_exp_f32_e32 v96, v96
	v_add_f32_e32 v2, v89, v2
	v_add_f32_e32 v2, v90, v2
	v_exp_f32_e32 v97, v97
	v_add_f32_e32 v2, v91, v2
	v_add_f32_e32 v2, v145, v2
	v_exp_f32_e32 v98, v98
	v_add_f32_e32 v2, v147, v2
	v_add_f32_e32 v2, v180, v2
	v_exp_f32_e32 v99, v99
	v_add_f32_e32 v2, v181, v2
	v_add_f32_e32 v2, v96, v2
	v_add_f32_e32 v2, v97, v2
	v_add_f32_e32 v2, v98, v2
	v_add_f32_e32 v2, v99, v2
	v_fmac_f32_e32 v2, v178, v0
	v_add3_u32 v0, v135, v169, v168
	v_cvt_pk_bf16_f32 v95, v90, v91
	v_cvt_pk_bf16_f32 v87, v98, v99
	v_cvt_pk_bf16_f32 v98, v183, v101
	v_cvt_pk_bf16_f32 v91, v114, v115
	v_add_u32_e32 v101, v0, v174
	v_add_u32_e32 v114, v0, v175
	v_cvt_pk_bf16_f32 v94, v88, v89
	v_cvt_pk_bf16_f32 v86, v96, v97
	v_cvt_pk_bf16_f32 v96, v104, v105
	v_cvt_pk_bf16_f32 v97, v106, v107
	v_cvt_pk_bf16_f32 v99, v102, v103
	v_cvt_pk_bf16_f32 v88, v108, v109
	ds_read2st64_b64 v[102:105], v101 offset0:32 offset1:36
	ds_read2st64_b64 v[106:109], v114 offset0:32 offset1:36
	v_cvt_pk_bf16_f32 v90, v112, v113
	v_cvt_pk_bf16_f32 v92, v137, v139
	v_cvt_pk_bf16_f32 v93, v141, v143
	v_cvt_pk_bf16_f32 v89, v110, v111
	s_waitcnt lgkmcnt(0)
	v_mov_b32_e32 v112, v106
	v_mov_b32_e32 v113, v107
	v_mov_b32_e32 v106, v104
	v_mov_b32_e32 v107, v105
	v_mov_b32_e32 v110, v102
	v_mov_b32_e32 v111, v103
	v_mfma_f32_16x16x32_bf16 v[72:75], v[106:109], v[92:95], v[72:75]
	v_cvt_pk_bf16_f32 v84, v145, v147
	v_cvt_pk_bf16_f32 v85, v180, v181
	s_add_i32 s31, s31, 1
	v_mfma_f32_16x16x32_bf16 v[68:71], v[106:109], v[96:99], v[68:71]
	ds_read2st64_b64 v[102:105], v101 offset0:40 offset1:44
	ds_read2st64_b64 v[106:109], v114 offset0:40 offset1:44
	s_add_i32 s84, s84, 64
	s_add_i32 s30, s30, 0x8000
	v_mfma_f32_16x16x32_bf16 v[80:83], v[110:113], v[92:95], v[80:83]
	s_mov_b64 s[0:1], 0x4000
	v_lshl_add_u64 v[126:127], v[126:127], 0, s[70:71]
	v_lshl_add_u64 v[128:129], v[128:129], 0, s[0:1]
	v_mfma_f32_16x16x32_bf16 v[76:79], v[110:113], v[96:99], v[76:79]
	s_waitcnt lgkmcnt(0)
	v_mov_b32_e32 v112, v106
	v_mov_b32_e32 v113, v107
	v_mov_b32_e32 v106, v104
	v_mov_b32_e32 v107, v105
	v_mov_b32_e32 v110, v102
	v_mov_b32_e32 v111, v103
	v_mfma_f32_16x16x32_bf16 v[56:59], v[106:109], v[92:95], v[56:59]
	s_cmp_lg_u32 s31, 20
	v_mfma_f32_16x16x32_bf16 v[52:55], v[106:109], v[96:99], v[52:55]
	ds_read2st64_b64 v[102:105], v101 offset0:48 offset1:52
	ds_read2st64_b64 v[106:109], v114 offset0:48 offset1:52
	v_mfma_f32_16x16x32_bf16 v[64:67], v[110:113], v[92:95], v[64:67]
	v_mfma_f32_16x16x32_bf16 v[60:63], v[110:113], v[96:99], v[60:63]
	s_waitcnt lgkmcnt(0)
	v_mov_b32_e32 v112, v106
	v_mov_b32_e32 v113, v107
	v_mov_b32_e32 v106, v104
	v_mov_b32_e32 v107, v105
	v_mov_b32_e32 v110, v102
	v_mov_b32_e32 v111, v103
	v_mfma_f32_16x16x32_bf16 v[40:43], v[106:109], v[92:95], v[40:43]
	v_mfma_f32_16x16x32_bf16 v[36:39], v[106:109], v[96:99], v[36:39]
	ds_read2st64_b64 v[102:105], v101 offset0:56 offset1:60
	ds_read2st64_b64 v[106:109], v114 offset0:56 offset1:60
	v_add_u32_e32 v101, v0, v176
	v_mfma_f32_16x16x32_bf16 v[48:51], v[110:113], v[92:95], v[48:51]
	v_add_u32_e32 v0, v0, v177
	v_mfma_f32_16x16x32_bf16 v[44:47], v[110:113], v[96:99], v[44:47]
	s_waitcnt lgkmcnt(0)
	v_mov_b32_e32 v110, v102
	v_mov_b32_e32 v111, v103
	v_mov_b32_e32 v112, v106
	v_mov_b32_e32 v113, v107
	v_mov_b32_e32 v106, v104
	v_mov_b32_e32 v107, v105
	v_mfma_f32_16x16x32_bf16 v[32:35], v[110:113], v[92:95], v[32:35]
	v_mfma_f32_16x16x32_bf16 v[20:23], v[110:113], v[96:99], v[20:23]
	v_mfma_f32_16x16x32_bf16 v[24:27], v[106:109], v[92:95], v[24:27]
	ds_read2st64_b64 v[92:95], v101 offset0:32 offset1:36
	s_waitcnt lgkmcnt(0)
	v_mov_b32_e32 v102, v92
	v_mfma_f32_16x16x32_bf16 v[28:31], v[106:109], v[96:99], v[28:31]
	ds_read2st64_b64 v[96:99], v0 offset0:32 offset1:36
	v_mov_b32_e32 v103, v93
	s_waitcnt lgkmcnt(0)
	v_mov_b32_e32 v104, v96
	v_mov_b32_e32 v105, v97
	v_mov_b32_e32 v96, v94
	v_mov_b32_e32 v97, v95
	v_mfma_f32_16x16x32_bf16 v[80:83], v[102:105], v[84:87], v[80:83]
	s_nop 0
	v_mfma_f32_16x16x32_bf16 v[72:75], v[96:99], v[84:87], v[72:75]
	v_mfma_f32_16x16x32_bf16 v[68:71], v[96:99], v[88:91], v[68:71]
	ds_read2st64_b64 v[92:95], v101 offset0:40 offset1:44
	ds_read2st64_b64 v[96:99], v0 offset0:40 offset1:44
	v_mfma_f32_16x16x32_bf16 v[76:79], v[102:105], v[88:91], v[76:79]
	s_waitcnt lgkmcnt(0)
	v_mov_b32_e32 v102, v92
	v_mov_b32_e32 v104, v96
	v_mov_b32_e32 v105, v97
	v_mov_b32_e32 v96, v94
	v_mov_b32_e32 v97, v95
	v_mov_b32_e32 v103, v93
	s_nop 0
	v_mfma_f32_16x16x32_bf16 v[56:59], v[96:99], v[84:87], v[56:59]
	v_mfma_f32_16x16x32_bf16 v[52:55], v[96:99], v[88:91], v[52:55]
	ds_read2st64_b64 v[92:95], v101 offset0:48 offset1:52
	ds_read2st64_b64 v[96:99], v0 offset0:48 offset1:52
	v_mfma_f32_16x16x32_bf16 v[64:67], v[102:105], v[84:87], v[64:67]
	v_mfma_f32_16x16x32_bf16 v[60:63], v[102:105], v[88:91], v[60:63]
	s_waitcnt lgkmcnt(0)
	v_mov_b32_e32 v104, v96
	v_mov_b32_e32 v105, v97
	v_mov_b32_e32 v96, v94
	v_mov_b32_e32 v97, v95
	v_mov_b32_e32 v102, v92
	v_mov_b32_e32 v103, v93
	v_mfma_f32_16x16x32_bf16 v[40:43], v[96:99], v[84:87], v[40:43]
	v_mfma_f32_16x16x32_bf16 v[36:39], v[96:99], v[88:91], v[36:39]
	ds_read2st64_b64 v[92:95], v101 offset0:56 offset1:60
	ds_read2st64_b64 v[96:99], v0 offset0:56 offset1:60
	v_mfma_f32_16x16x32_bf16 v[48:51], v[102:105], v[84:87], v[48:51]
	v_mfma_f32_16x16x32_bf16 v[44:47], v[102:105], v[88:91], v[44:47]
	s_waitcnt lgkmcnt(0)
	v_mov_b32_e32 v102, v92
	v_mov_b32_e32 v103, v93
	v_mov_b32_e32 v104, v96
	v_mov_b32_e32 v105, v97
	v_mov_b32_e32 v96, v94
	v_mov_b32_e32 v97, v95
	v_mfma_f32_16x16x32_bf16 v[32:35], v[102:105], v[84:87], v[32:35]
	v_mfma_f32_16x16x32_bf16 v[20:23], v[102:105], v[88:91], v[20:23]
	v_mfma_f32_16x16x32_bf16 v[24:27], v[96:99], v[84:87], v[24:27]
	v_mfma_f32_16x16x32_bf16 v[28:31], v[96:99], v[88:91], v[28:31]
	s_cbranch_scc0 .LBB0_482
	v_mov_b32_e32 v178, v2
	v_mov_b32_e32 v179, v100
	v_mov_b32_e32 v100, v3
	v_mov_b32_e32 v181, v133
	s_branch .LBB0_614

.LBB0_677:
	s_or_b64 exec, exec, s[0:1]
	s_lshl_b32 s47, s46, 1
	v_readlane_b32 s0, v254, 53
	s_add_u32 s0, s0, s76
	v_readlane_b32 s1, v254, 54
	s_addc_u32 s1, s1, s77
	v_readlane_b32 s76, v255, 15
	s_waitcnt lgkmcnt(0)
	s_barrier
	v_readlane_b32 s77, v255, 16
	s_mov_b32 s32, 1
	s_branch .LBB0_681

.LBB0_681:
	s_barrier
	s_and_saveexec_b64 s[4:5], s[6:7]
	s_cbranch_execz .LBB0_685
	s_cmp_eq_u32 s32, 0
	s_cbranch_scc1 .Lq2_dyn
	s_mov_b32 s32, 0
	v_readlane_b32 s2, v254, 0
	s_nop 1
	v_mov_b32_e32 v0, s2
	ds_write_b32 v1, v0
	s_branch .LBB0_685
.Lq2_dyn:
	s_mov_b64 s[56:57], exec
	v_mbcnt_lo_u32_b32 v0, s56, 0
	v_mbcnt_hi_u32_b32 v0, s57, v0
	v_cmp_eq_u32_e32 vcc, 0, v0
	s_and_saveexec_b64 s[30:31], vcc
	s_cbranch_execz .LBB0_684
	s_bcnt1_i32_b64 s2, s[56:57]
	v_mov_b32_e32 v2, s2
	global_atomic_add v2, v1, v2, s[62:63] offset:256 sc0
.LBB0_684:
	s_or_b64 exec, exec, s[30:31]
	s_waitcnt vmcnt(0)
	v_readfirstlane_b32 s2, v2
	s_nop 1
	v_add_u32_e32 v0, s2, v0
	v_add_u32_e32 v0, s33, v0
	ds_write_b32 v1, v0
